# speedup vs baseline: 1.0369x; 1.0132x over previous
; template <bool MLA> ...
;     ...
;   int kt = nkt - 1;
;   TILE_DMA(kt * 64, 0);
;     ...
;     const int buf = it & 1;
;     asm volatile("s_waitcnt vmcnt(0)" ::: "memory");
;     __syncthreads();
;     if (kt > 0) TILE_DMA((kt - 1) * 64, buf ^ 1);
;     const int k0 = kt * 64;
;     if (k0 < bmax) {
.Lmlp_inactive:
	s_or_b64 exec, exec, s[0:1]
	s_cmp_lt_i32 s93, 1
	s_cbranch_scc1 .LBB0_367
	s_lshl_b32 s0, s39, 14
	s_xor_b32 s0, s0, 0x4000
	v_add_u32_e32 v66, s94, v222
	v_ashrrev_i32_e32 v67, 31, v66
	v_add_u32_e32 v68, s0, v209
	v_lshlrev_b64 v[66:67], 11, v[66:67]
	v_readfirstlane_b32 s0, v68
	v_lshl_add_u64 v[66:67], v[148:149], 0, v[66:67]
	s_mov_b32 m0, s0
	v_add_u32_e32 v68, 0x2000, v68
	global_load_lds_dwordx4 v[66:67], off
	v_add_u32_e32 v66, s94, v221
	v_ashrrev_i32_e32 v67, 31, v66
	v_readfirstlane_b32 s0, v68
	v_lshlrev_b64 v[66:67], 11, v[66:67]
	s_mov_b32 m0, s0
	s_xor_b32 s0, s39, 1
	v_lshl_add_u64 v[66:67], v[148:149], 0, v[66:67]
	s_mulk_i32 s0, 0x6000
	global_load_lds_dwordx4 v[66:67], off
	v_add_u32_e32 v66, s94, v220
	v_add_u32_e32 v68, s0, v209
	v_ashrrev_i32_e32 v67, 31, v66
	v_add_u32_e32 v69, 0x8000, v68
	v_lshlrev_b64 v[66:67], v152, v[66:67]
	v_readfirstlane_b32 s0, v69
	v_lshl_add_u64 v[66:67], v[154:155], 0, v[66:67]
	s_mov_b32 m0, s0
	v_add_u32_e32 v69, 0xa000, v68
	global_load_lds_dwordx4 v[66:67], off
	v_add_u32_e32 v66, s94, v219
	v_ashrrev_i32_e32 v67, 31, v66
	v_lshlrev_b64 v[66:67], v156, v[66:67]
	v_readfirstlane_b32 s0, v69
	v_lshl_add_u64 v[66:67], v[158:159], 0, v[66:67]
	s_mov_b32 m0, s0
	v_add_u32_e32 v68, 0xc000, v68
	global_load_lds_dwordx4 v[66:67], off
	v_add_u32_e32 v66, s94, v218
	v_ashrrev_i32_e32 v67, 31, v66
	v_lshlrev_b64 v[66:67], v150, v[66:67]
	v_readfirstlane_b32 s0, v68
	v_lshl_add_u64 v[66:67], v[160:161], 0, v[66:67]
	s_mov_b32 m0, s0
	s_nop 0
	global_load_lds_dwordx4 v[66:67], off
	s_branch .LBB0_367

; template <bool MLA> ...
;     ...
;   int kt = nkt - 1;
;   TILE_DMA(kt * 64, 0);
;     ...
;     const int buf = it & 1;
;     asm volatile("s_waitcnt vmcnt(0)" ::: "memory");
;     __syncthreads();
;     if (kt > 0) TILE_DMA((kt - 1) * 64, buf ^ 1);
;     const int k0 = kt * 64;
;     if (k0 < bmax) {
;       const char* Ks = K_lds + buf * SHM_K + r32 * KP;
;       f32x16 p0, p1;
; #pragma unroll
;       for (int r = 0; r < 16; ++r) { p0[r] = 0.f; p1[r] = 0.f; }
; #pragma unroll
;       for (int d0 = 0; d0 < ND0; ++d0) { const int off = kq4[d0 & 3] + (d0 >> 2) * 128;
;         bf16x8 b0 = *reinterpret_cast<const bf16x8*>(Ks + off);
;         bf16x8 b1 = *reinterpret_cast<const bf16x8*>(Ks + off + 32 * KP);
;         p0 = __builtin_amdgcn_mfma_f32_32x32x16_bf16(b0, qr[d0], p0, 0, 0, 0);
;         p1 = __builtin_amdgcn_mfma_f32_32x32x16_bf16(b1, qr[d0], p1, 0, 0, 0); }
.LBB0_370:
	s_add_i32 s12, s72, s94
	s_addk_i32 s12, 0xc0
	v_cmp_lt_i32_e32 vcc, s12, v215
	s_and_saveexec_b64 s[0:1], vcc
	s_cbranch_execz .Lmlp_inactive
	s_mul_i32 s13, s39, 0x6000
	v_add_u32_e32 v223, s13, v216
	v_add_u32_e32 v228, v223, v213
	v_add_u32_e32 v229, v223, v212
	v_add_u32_e32 v230, v223, v211
	v_add_u32_e32 v223, v223, v210
	ds_read_b128 v[224:227], v228 offset:32768
	ds_read_b128 v[232:235], v229 offset:32768
	ds_read_b128 v[236:239], v228 offset:45056
	ds_read_b128 v[240:243], v229 offset:45056
	v_cmp_ge_i32_e32 vcc, s12, v214
	s_waitcnt lgkmcnt(3)
	v_mfma_f32_32x32x16_bf16 v[66:81], v[224:227], v[142:145], 0
	ds_read_b128 v[224:227], v230 offset:32768
	s_waitcnt lgkmcnt(3)
	v_mfma_f32_32x32x16_bf16 v[66:81], v[232:235], v[138:141], v[66:81]
	ds_read_b128 v[232:235], v230 offset:45056
	s_waitcnt lgkmcnt(3)
	v_mfma_f32_32x32x16_bf16 v[82:97], v[236:239], v[142:145], 0
	ds_read_b128 v[236:239], v223 offset:32768
	s_waitcnt lgkmcnt(3)
	v_mfma_f32_32x32x16_bf16 v[82:97], v[240:243], v[138:141], v[82:97]
	ds_read_b128 v[240:243], v223 offset:45056
	s_waitcnt lgkmcnt(3)
	v_mfma_f32_32x32x16_bf16 v[66:81], v[224:227], v[134:137], v[66:81]
	ds_read_b128 v[224:227], v228 offset:32896
	s_waitcnt lgkmcnt(3)
	v_mfma_f32_32x32x16_bf16 v[82:97], v[232:235], v[134:137], v[82:97]
	ds_read_b128 v[232:235], v228 offset:45184
	s_waitcnt lgkmcnt(3)
	v_mfma_f32_32x32x16_bf16 v[66:81], v[236:239], v[130:133], v[66:81]
	ds_read_b128 v[236:239], v229 offset:32896
	s_waitcnt lgkmcnt(3)
	v_mfma_f32_32x32x16_bf16 v[82:97], v[240:243], v[130:133], v[82:97]
	ds_read_b128 v[240:243], v229 offset:45184
	s_waitcnt lgkmcnt(3)
	v_mfma_f32_32x32x16_bf16 v[66:81], v[224:227], v[126:129], v[66:81]
	ds_read_b128 v[224:227], v230 offset:32896
	s_waitcnt lgkmcnt(3)
	v_mfma_f32_32x32x16_bf16 v[82:97], v[232:235], v[126:129], v[82:97]
	ds_read_b128 v[232:235], v230 offset:45184
	s_waitcnt lgkmcnt(3)
	v_mfma_f32_32x32x16_bf16 v[66:81], v[236:239], v[122:125], v[66:81]
	ds_read_b128 v[236:239], v223 offset:32896
	s_waitcnt lgkmcnt(3)
	v_mfma_f32_32x32x16_bf16 v[82:97], v[240:243], v[122:125], v[82:97]
	ds_read_b128 v[240:243], v223 offset:45184
	s_waitcnt lgkmcnt(3)
	v_mfma_f32_32x32x16_bf16 v[66:81], v[224:227], v[118:121], v[66:81]
	ds_read_b128 v[224:227], v228 offset:33024
	s_waitcnt lgkmcnt(3)
	v_mfma_f32_32x32x16_bf16 v[82:97], v[232:235], v[118:121], v[82:97]
	ds_read_b128 v[232:235], v228 offset:45312
	s_waitcnt lgkmcnt(3)
	v_mfma_f32_32x32x16_bf16 v[66:81], v[236:239], v[114:117], v[66:81]
	ds_read_b128 v[236:239], v229 offset:33024
	s_waitcnt lgkmcnt(3)
	v_mfma_f32_32x32x16_bf16 v[82:97], v[240:243], v[114:117], v[82:97]
	ds_read_b128 v[240:243], v229 offset:45312
	s_waitcnt lgkmcnt(3)
	v_mfma_f32_32x32x16_bf16 v[66:81], v[224:227], v[110:113], v[66:81]
	ds_read_b128 v[224:227], v230 offset:33024
	s_waitcnt lgkmcnt(3)
	v_mfma_f32_32x32x16_bf16 v[82:97], v[232:235], v[110:113], v[82:97]
	ds_read_b128 v[232:235], v230 offset:45312
	s_waitcnt lgkmcnt(3)
	v_mfma_f32_32x32x16_bf16 v[66:81], v[236:239], v[106:109], v[66:81]
	ds_read_b128 v[236:239], v223 offset:33024
	s_waitcnt lgkmcnt(3)
	v_mfma_f32_32x32x16_bf16 v[82:97], v[240:243], v[106:109], v[82:97]
	ds_read_b128 v[240:243], v223 offset:45312
	s_waitcnt lgkmcnt(3)
	v_mfma_f32_32x32x16_bf16 v[66:81], v[224:227], v[102:105], v[66:81]
	s_waitcnt lgkmcnt(2)
	v_mfma_f32_32x32x16_bf16 v[82:97], v[232:235], v[102:105], v[82:97]
	s_waitcnt lgkmcnt(1)
	v_mfma_f32_32x32x16_bf16 v[66:81], v[236:239], v[98:101], v[66:81]
	s_waitcnt lgkmcnt(0)
	v_mfma_f32_32x32x16_bf16 v[82:97], v[240:243], v[98:101], v[82:97]
	s_cmp_lt_i32 s93, 1
	s_cbranch_scc1 .Lmlp_nodma
	s_lshl_b32 s13, s39, 14
	s_xor_b32 s13, s13, 0x4000
	v_add_u32_e32 v244, s94, v222
	v_ashrrev_i32_e32 v245, 31, v244
	v_add_u32_e32 v246, s13, v209
	v_lshlrev_b64 v[244:245], 11, v[244:245]
	v_readfirstlane_b32 s13, v246
	v_lshl_add_u64 v[244:245], v[148:149], 0, v[244:245]
	s_mov_b32 m0, s13
	v_add_u32_e32 v246, 0x2000, v246
	global_load_lds_dwordx4 v[244:245], off
	v_add_u32_e32 v244, s94, v221
	v_ashrrev_i32_e32 v245, 31, v244
	v_readfirstlane_b32 s13, v246
	v_lshlrev_b64 v[244:245], 11, v[244:245]
	s_mov_b32 m0, s13
	s_xor_b32 s13, s39, 1
	v_lshl_add_u64 v[244:245], v[148:149], 0, v[244:245]
	s_mulk_i32 s13, 0x6000
	global_load_lds_dwordx4 v[244:245], off
	v_add_u32_e32 v244, s94, v220
	v_add_u32_e32 v246, s13, v209
	v_ashrrev_i32_e32 v245, 31, v244
	v_add_u32_e32 v247, 0x8000, v246
	v_lshlrev_b64 v[244:245], v152, v[244:245]
	v_readfirstlane_b32 s13, v247
	v_lshl_add_u64 v[244:245], v[154:155], 0, v[244:245]
	s_mov_b32 m0, s13
	v_add_u32_e32 v247, 0xa000, v246
	global_load_lds_dwordx4 v[244:245], off
	v_add_u32_e32 v244, s94, v219
	v_ashrrev_i32_e32 v245, 31, v244
	v_lshlrev_b64 v[244:245], v156, v[244:245]
	v_readfirstlane_b32 s13, v247
	v_lshl_add_u64 v[244:245], v[158:159], 0, v[244:245]
	s_mov_b32 m0, s13
	v_add_u32_e32 v246, 0xc000, v246
	global_load_lds_dwordx4 v[244:245], off
	v_add_u32_e32 v244, s94, v218
	v_ashrrev_i32_e32 v245, 31, v244
	v_lshlrev_b64 v[244:245], v150, v[244:245]
	v_readfirstlane_b32 s13, v246
	v_lshl_add_u64 v[244:245], v[160:161], 0, v[244:245]
	s_mov_b32 m0, s13
	s_nop 0
	global_load_lds_dwordx4 v[244:245], off
; template <bool MLA> ...
;     ...
;         float pmax = -INFINITY;
;         if (needmask) {
; #pragma unroll
;           for (int r = 0; r < 16; ++r) { const int key = kb + (r & 3) + 8 * (r >> 2);
;             p0[r] = key < bound ? p0[r] : -INFINITY; p1[r] = key + 32 < bound ? p1[r] : -INFINITY;
;             pmax = fmaxf(pmax, fmaxf(p0[r], p1[r])); }
.Lmlp_nodma:
	s_nop 1
	s_and_saveexec_b64 s[12:13], vcc
	s_xor_b64 s[12:13], exec, s[12:13]
	s_cbranch_execz .LBB0_373
	v_add_u32_e32 v223, s94, v217
	v_cmp_lt_i32_e32 vcc, v223, v192
	s_mov_b32 s4, 0xff800000
	s_nop 2
	v_cndmask_b32_e32 v66, v188, v66, vcc
	v_cmp_lt_i32_e32 vcc, v223, v207
	v_max_f32_e32 v225, v66, v66
	s_nop 0
	v_cndmask_b32_e32 v82, v188, v82, vcc
	v_cmp_lt_i32_e32 vcc, v223, v206
	v_max_f32_e32 v224, v82, v82
	v_max_f32_e32 v224, v225, v224
	v_cndmask_b32_e32 v67, v188, v67, vcc
	v_cmp_lt_i32_e32 vcc, v223, v205
	v_max_f32_e32 v226, v67, v67
	s_nop 0
	v_cndmask_b32_e32 v83, v188, v83, vcc
	v_cmp_lt_i32_e32 vcc, v223, v204
	v_max_f32_e32 v225, v83, v83
	v_max_f32_e32 v225, v226, v225
	v_cndmask_b32_e32 v68, v188, v68, vcc
	v_cmp_lt_i32_e32 vcc, v223, v203
	v_max3_f32 v224, v224, s4, v225
	v_max_f32_e32 v226, v68, v68
	v_cndmask_b32_e32 v84, v188, v84, vcc
	v_cmp_lt_i32_e32 vcc, v223, v202
	v_max_f32_e32 v225, v84, v84
	v_max_f32_e32 v225, v226, v225
	v_cndmask_b32_e32 v69, v188, v69, vcc
	v_cmp_lt_i32_e32 vcc, v223, v201
	v_max_f32_e32 v227, v69, v69
	s_nop 0
	v_cndmask_b32_e32 v85, v188, v85, vcc
	v_cmp_lt_i32_e32 vcc, v223, v200
	v_max_f32_e32 v226, v85, v85
	v_max_f32_e32 v226, v227, v226
	v_cndmask_b32_e32 v70, v188, v70, vcc
	v_cmp_lt_i32_e32 vcc, v223, v199
	v_max3_f32 v224, v224, v225, v226
	v_max_f32_e32 v226, v70, v70
	v_cndmask_b32_e32 v86, v188, v86, vcc
	v_cmp_lt_i32_e32 vcc, v223, v198
	v_max_f32_e32 v225, v86, v86
	v_max_f32_e32 v225, v226, v225
	v_cndmask_b32_e32 v71, v188, v71, vcc
	v_cmp_lt_i32_e32 vcc, v223, v197
	v_max_f32_e32 v227, v71, v71
	s_nop 0
	v_cndmask_b32_e32 v87, v188, v87, vcc
	v_cmp_lt_i32_e32 vcc, v223, v196
	v_max_f32_e32 v226, v87, v87
	v_max_f32_e32 v226, v227, v226
	v_cndmask_b32_e32 v72, v188, v72, vcc
	v_cmp_lt_i32_e32 vcc, v223, v195
	v_max3_f32 v224, v224, v225, v226
	v_max_f32_e32 v226, v72, v72
	v_cndmask_b32_e32 v88, v188, v88, vcc
	v_cmp_lt_i32_e32 vcc, v223, v194
	v_max_f32_e32 v225, v88, v88
	v_max_f32_e32 v225, v226, v225
	v_cndmask_b32_e32 v73, v188, v73, vcc
	v_cmp_lt_i32_e32 vcc, v223, v193
	v_max_f32_e32 v227, v73, v73
	s_nop 0
	v_cndmask_b32_e32 v89, v188, v89, vcc
	v_cmp_lt_i32_e32 vcc, v223, v183
	v_max_f32_e32 v226, v89, v89
	v_max_f32_e32 v226, v227, v226
	v_cndmask_b32_e32 v74, v188, v74, vcc
	v_cmp_lt_i32_e32 vcc, v223, v182
	v_max3_f32 v224, v224, v225, v226
	v_max_f32_e32 v226, v74, v74
	v_cndmask_b32_e32 v90, v188, v90, vcc
	v_cmp_lt_i32_e32 vcc, v223, v181
	v_max_f32_e32 v225, v90, v90
	v_max_f32_e32 v225, v226, v225
	v_cndmask_b32_e32 v75, v188, v75, vcc
	v_cmp_lt_i32_e32 vcc, v223, v180
	v_max_f32_e32 v227, v75, v75
	s_nop 0
	v_cndmask_b32_e32 v91, v188, v91, vcc
	v_cmp_lt_i32_e32 vcc, v223, v179
	v_max_f32_e32 v226, v91, v91
	v_max_f32_e32 v226, v227, v226
	v_cndmask_b32_e32 v76, v188, v76, vcc
	v_cmp_lt_i32_e32 vcc, v223, v178
	v_max3_f32 v224, v224, v225, v226
	v_max_f32_e32 v226, v76, v76
	v_cndmask_b32_e32 v92, v188, v92, vcc
	v_cmp_lt_i32_e32 vcc, v223, v177
	v_max_f32_e32 v225, v92, v92
	v_max_f32_e32 v225, v226, v225
	v_cndmask_b32_e32 v77, v188, v77, vcc
	v_cmp_lt_i32_e32 vcc, v223, v176
	v_max_f32_e32 v227, v77, v77
	s_nop 0
	v_cndmask_b32_e32 v93, v188, v93, vcc
	v_cmp_lt_i32_e32 vcc, v223, v175
	v_max_f32_e32 v226, v93, v93
	v_max_f32_e32 v226, v227, v226
	v_cndmask_b32_e32 v78, v188, v78, vcc
	v_cmp_lt_i32_e32 vcc, v223, v174
	v_max3_f32 v224, v224, v225, v226
	v_max_f32_e32 v226, v78, v78
	v_cndmask_b32_e32 v94, v188, v94, vcc
	v_cmp_lt_i32_e32 vcc, v223, v173
	v_max_f32_e32 v225, v94, v94
	v_max_f32_e32 v225, v226, v225
	v_cndmask_b32_e32 v79, v188, v79, vcc
	v_cmp_lt_i32_e32 vcc, v223, v172
	v_max_f32_e32 v227, v79, v79
	s_nop 0
	v_cndmask_b32_e32 v95, v188, v95, vcc
	v_cmp_lt_i32_e32 vcc, v223, v171
	v_max_f32_e32 v226, v95, v95
	v_max_f32_e32 v226, v227, v226
	v_cndmask_b32_e32 v80, v188, v80, vcc
	v_cmp_lt_i32_e32 vcc, v223, v170
	v_max3_f32 v224, v224, v225, v226
	v_max_f32_e32 v226, v80, v80
	v_cndmask_b32_e32 v96, v188, v96, vcc
	v_cmp_lt_i32_e32 vcc, v223, v169
	v_max_f32_e32 v225, v96, v96
	v_max_f32_e32 v225, v226, v225
	v_cndmask_b32_e32 v81, v188, v81, vcc
	v_cmp_lt_i32_e32 vcc, v223, v168
	v_max_f32_e32 v226, v81, v81
	s_nop 0
	v_cndmask_b32_e32 v97, v188, v97, vcc
	v_max_f32_e32 v223, v97, v97
	v_max_f32_e32 v223, v226, v223
	v_max3_f32 v223, v224, v225, v223

; DEVI int crow(int r, int hi) { return (r & 3) + 8 * (r >> 2) + 4 * hi; }
; template <bool MLA> ...
;     ...
;   if (wact) {
;     float rli[16];
;     if (MLA) {
;       if (hi == 0) al_l[r32] = l_reg;
;       asm volatile("s_waitcnt lgkmcnt(0)" ::: "memory");
; #pragma unroll
;       for (int r = 0; r < 16; ++r) rli[r] = __builtin_amdgcn_rcpf(al_l[crow(r, hi)]);
;     } else {
; #pragma unroll
;       for (int r = 0; r < 16; ++r) rli[r] = 1.f;
;     }
; #pragma unroll
;     for (int r = 0; r < 16; ++r) { const int orow = first + crow(r, hi);
;       if (orow < nrows) {
; #pragma unroll
;         for (int d0 = 0; d0 < 4; ++d0) Ob[(long)orow * ldo + d0 * 32 + r32] = __float2bfloat16(o[d0][r] * rli[r]); } }
.LBB0_388:
	s_or_b64 exec, exec, s[0:1]
	s_and_saveexec_b64 s[0:1], s[6:7]
	s_cbranch_execz .LBB0_423
	s_and_saveexec_b64 s[6:7], s[8:9]
	ds_write_b32 v163, v166
	s_or_b64 exec, exec, s[6:7]
	s_waitcnt lgkmcnt(0)
	v_add_u32_e32 v81, v157, v32
	v_readlane_b32 s6, v254, 47
	ds_read2_b32 v[82:83], v81 offset0:1 offset1:2
	ds_read_b32 v86, v81 offset:12
	ds_read_b128 v[74:77], v81 offset:32
	ds_read_b128 v[70:73], v81 offset:64
	ds_read_b128 v[66:69], v81 offset:96
	v_readlane_b32 s7, v254, 48
	s_lshl_b64 s[6:7], s[6:7], 12
	v_readlane_b32 s4, v255, 25
	s_add_u32 s6, s4, s6
	v_readlane_b32 s4, v255, 44
	s_addc_u32 s7, s4, s7
	s_lshl_b32 s8, s22, 1
	s_add_u32 s6, s6, s8
	s_addc_u32 s7, s7, 0
	v_or_b32_e32 v80, v162, v153
	v_lshlrev_b32_e32 v32, 1, v151
	v_lshl_add_u64 v[78:79], s[6:7], 0, v[32:33]
	ds_read_b32 v87, v81
	s_waitcnt lgkmcnt(0)
	v_rcp_f32_e32 v87, v87
	v_rcp_f32_e32 v82, v82
	v_rcp_f32_e32 v83, v83
	v_rcp_f32_e32 v86, v86
	v_rcp_f32_e32 v74, v74
	v_rcp_f32_e32 v75, v75
	v_rcp_f32_e32 v76, v76
	v_rcp_f32_e32 v77, v77
	v_rcp_f32_e32 v70, v70
	v_rcp_f32_e32 v71, v71
	v_rcp_f32_e32 v72, v72
	v_rcp_f32_e32 v73, v73
	v_rcp_f32_e32 v66, v66
	v_rcp_f32_e32 v67, v67
	v_rcp_f32_e32 v68, v68
	v_rcp_f32_e32 v69, v69
	s_nop 0
	s_mov_b32 s6, 0xaaaaaaaa
	s_mov_b32 s7, 0xaaaaaaaa
	v_mov_b32_e32 v224, 0xffe
	v_cndmask_b32_e64 v224, 0, v224, s[6:7]
	v_mov_b32_e32 v225, 0
	v_lshl_add_u64 v[78:79], v[78:79], 0, v[224:225]
	v_mov_b32_e32 v226, v80
	v_ashrrev_i32_e32 v227, 31, v226
	v_lshlrev_b64 v[226:227], 12, v[226:227]
	v_lshl_add_u64 v[228:229], v[78:79], 0, v[226:227]
	v_mul_f32_e32 v0, v0, v87
	v_mul_f32_e32 v1, v1, v82
	v_mul_f32_e32 v50, v50, v87
	v_mul_f32_e32 v51, v51, v82
	v_mul_f32_e32 v34, v34, v87
	v_mul_f32_e32 v35, v35, v82
	v_mul_f32_e32 v16, v16, v87
	v_mul_f32_e32 v17, v17, v82
	v_cndmask_b32_e64 v230, v1, v0, s[6:7]
	v_cndmask_b32_e64 v231, v51, v50, s[6:7]
	v_cndmask_b32_e64 v232, v35, v34, s[6:7]
	v_cndmask_b32_e64 v233, v17, v16, s[6:7]
	v_mov_b32_dpp v234, v230 quad_perm:[1,0,3,2] row_mask:0xf bank_mask:0xf
	v_mov_b32_dpp v235, v231 quad_perm:[1,0,3,2] row_mask:0xf bank_mask:0xf
	v_mov_b32_dpp v236, v232 quad_perm:[1,0,3,2] row_mask:0xf bank_mask:0xf
	v_mov_b32_dpp v237, v233 quad_perm:[1,0,3,2] row_mask:0xf bank_mask:0xf
	v_cndmask_b32_e64 v238, v0, v234, s[6:7]
	v_cndmask_b32_e64 v239, v234, v1, s[6:7]
	v_cvt_pk_bf16_f32 v240, v238, v239
	v_cndmask_b32_e64 v238, v50, v235, s[6:7]
	v_cndmask_b32_e64 v239, v235, v51, s[6:7]
	v_cvt_pk_bf16_f32 v241, v238, v239
	v_cndmask_b32_e64 v238, v34, v236, s[6:7]
	v_cndmask_b32_e64 v239, v236, v35, s[6:7]
	v_cvt_pk_bf16_f32 v242, v238, v239
	v_cndmask_b32_e64 v238, v16, v237, s[6:7]
	v_cndmask_b32_e64 v239, v237, v17, s[6:7]
	v_cvt_pk_bf16_f32 v243, v238, v239
	global_store_dword v[228:229], v240, off offset:2048
	global_store_dword v[228:229], v241, off offset:2112
	global_store_dword v[228:229], v242, off offset:2176
	global_store_dword v[228:229], v243, off offset:2240
	v_or_b32_e32 v226, 2, v80
	v_ashrrev_i32_e32 v227, 31, v226
	v_lshlrev_b64 v[226:227], 12, v[226:227]
	v_lshl_add_u64 v[228:229], v[78:79], 0, v[226:227]
	v_mul_f32_e32 v2, v2, v83
	v_mul_f32_e32 v3, v3, v86
	v_mul_f32_e32 v52, v52, v83
	v_mul_f32_e32 v53, v53, v86
	v_mul_f32_e32 v36, v36, v83
	v_mul_f32_e32 v37, v37, v86
	v_mul_f32_e32 v18, v18, v83
	v_mul_f32_e32 v19, v19, v86
	v_cndmask_b32_e64 v230, v3, v2, s[6:7]
	v_cndmask_b32_e64 v231, v53, v52, s[6:7]
	v_cndmask_b32_e64 v232, v37, v36, s[6:7]
	v_cndmask_b32_e64 v233, v19, v18, s[6:7]
	v_mov_b32_dpp v234, v230 quad_perm:[1,0,3,2] row_mask:0xf bank_mask:0xf
	v_mov_b32_dpp v235, v231 quad_perm:[1,0,3,2] row_mask:0xf bank_mask:0xf
	v_mov_b32_dpp v236, v232 quad_perm:[1,0,3,2] row_mask:0xf bank_mask:0xf
	v_mov_b32_dpp v237, v233 quad_perm:[1,0,3,2] row_mask:0xf bank_mask:0xf
	v_cndmask_b32_e64 v238, v2, v234, s[6:7]
	v_cndmask_b32_e64 v239, v234, v3, s[6:7]
	v_cvt_pk_bf16_f32 v240, v238, v239
	v_cndmask_b32_e64 v238, v52, v235, s[6:7]
	v_cndmask_b32_e64 v239, v235, v53, s[6:7]
	v_cvt_pk_bf16_f32 v241, v238, v239
	v_cndmask_b32_e64 v238, v36, v236, s[6:7]
	v_cndmask_b32_e64 v239, v236, v37, s[6:7]
	v_cvt_pk_bf16_f32 v242, v238, v239
	v_cndmask_b32_e64 v238, v18, v237, s[6:7]
	v_cndmask_b32_e64 v239, v237, v19, s[6:7]
	v_cvt_pk_bf16_f32 v243, v238, v239
	global_store_dword v[228:229], v240, off offset:2048
	global_store_dword v[228:229], v241, off offset:2112
	global_store_dword v[228:229], v242, off offset:2176
	global_store_dword v[228:229], v243, off offset:2240
	v_or_b32_e32 v226, 8, v80
	v_ashrrev_i32_e32 v227, 31, v226
	v_lshlrev_b64 v[226:227], 12, v[226:227]
	v_lshl_add_u64 v[228:229], v[78:79], 0, v[226:227]
	v_mul_f32_e32 v4, v4, v74
	v_mul_f32_e32 v5, v5, v75
	v_mul_f32_e32 v54, v54, v74
	v_mul_f32_e32 v55, v55, v75
	v_mul_f32_e32 v38, v38, v74
	v_mul_f32_e32 v39, v39, v75
	v_mul_f32_e32 v20, v20, v74
	v_mul_f32_e32 v21, v21, v75
	v_cndmask_b32_e64 v230, v5, v4, s[6:7]
	v_cndmask_b32_e64 v231, v55, v54, s[6:7]
	v_cndmask_b32_e64 v232, v39, v38, s[6:7]
	v_cndmask_b32_e64 v233, v21, v20, s[6:7]
	v_mov_b32_dpp v234, v230 quad_perm:[1,0,3,2] row_mask:0xf bank_mask:0xf
	v_mov_b32_dpp v235, v231 quad_perm:[1,0,3,2] row_mask:0xf bank_mask:0xf
	v_mov_b32_dpp v236, v232 quad_perm:[1,0,3,2] row_mask:0xf bank_mask:0xf
	v_mov_b32_dpp v237, v233 quad_perm:[1,0,3,2] row_mask:0xf bank_mask:0xf
	v_cndmask_b32_e64 v238, v4, v234, s[6:7]
	v_cndmask_b32_e64 v239, v234, v5, s[6:7]
	v_cvt_pk_bf16_f32 v240, v238, v239
	v_cndmask_b32_e64 v238, v54, v235, s[6:7]
	v_cndmask_b32_e64 v239, v235, v55, s[6:7]
	v_cvt_pk_bf16_f32 v241, v238, v239
	v_cndmask_b32_e64 v238, v38, v236, s[6:7]
; DEVI int crow(int r, int hi) { return (r & 3) + 8 * (r >> 2) + 4 * hi; }
; template <bool MLA> ...
;     ...
; #pragma unroll
;     for (int r = 0; r < 16; ++r) { const int orow = first + crow(r, hi);
;       if (orow < nrows) {
; #pragma unroll
;         for (int d0 = 0; d0 < 4; ++d0) Ob[(long)orow * ldo + d0 * 32 + r32] = __float2bfloat16(o[d0][r] * rli[r]); } }
	v_cndmask_b32_e64 v239, v236, v39, s[6:7]
	v_cvt_pk_bf16_f32 v242, v238, v239
	v_cndmask_b32_e64 v238, v20, v237, s[6:7]
	v_cndmask_b32_e64 v239, v237, v21, s[6:7]
	v_cvt_pk_bf16_f32 v243, v238, v239
	global_store_dword v[228:229], v240, off offset:2048
	global_store_dword v[228:229], v241, off offset:2112
	global_store_dword v[228:229], v242, off offset:2176
	global_store_dword v[228:229], v243, off offset:2240
	v_or_b32_e32 v226, 10, v80
	v_ashrrev_i32_e32 v227, 31, v226
	v_lshlrev_b64 v[226:227], 12, v[226:227]
	v_lshl_add_u64 v[228:229], v[78:79], 0, v[226:227]
	v_mul_f32_e32 v6, v6, v76
	v_mul_f32_e32 v7, v7, v77
	v_mul_f32_e32 v56, v56, v76
	v_mul_f32_e32 v57, v57, v77
	v_mul_f32_e32 v40, v40, v76
	v_mul_f32_e32 v41, v41, v77
	v_mul_f32_e32 v22, v22, v76
	v_mul_f32_e32 v23, v23, v77
	v_cndmask_b32_e64 v230, v7, v6, s[6:7]
	v_cndmask_b32_e64 v231, v57, v56, s[6:7]
	v_cndmask_b32_e64 v232, v41, v40, s[6:7]
	v_cndmask_b32_e64 v233, v23, v22, s[6:7]
	v_mov_b32_dpp v234, v230 quad_perm:[1,0,3,2] row_mask:0xf bank_mask:0xf
	v_mov_b32_dpp v235, v231 quad_perm:[1,0,3,2] row_mask:0xf bank_mask:0xf
	v_mov_b32_dpp v236, v232 quad_perm:[1,0,3,2] row_mask:0xf bank_mask:0xf
	v_mov_b32_dpp v237, v233 quad_perm:[1,0,3,2] row_mask:0xf bank_mask:0xf
	v_cndmask_b32_e64 v238, v6, v234, s[6:7]
	v_cndmask_b32_e64 v239, v234, v7, s[6:7]
	v_cvt_pk_bf16_f32 v240, v238, v239
	v_cndmask_b32_e64 v238, v56, v235, s[6:7]
	v_cndmask_b32_e64 v239, v235, v57, s[6:7]
	v_cvt_pk_bf16_f32 v241, v238, v239
	v_cndmask_b32_e64 v238, v40, v236, s[6:7]
	v_cndmask_b32_e64 v239, v236, v41, s[6:7]
	v_cvt_pk_bf16_f32 v242, v238, v239
	v_cndmask_b32_e64 v238, v22, v237, s[6:7]
	v_cndmask_b32_e64 v239, v237, v23, s[6:7]
	v_cvt_pk_bf16_f32 v243, v238, v239
	global_store_dword v[228:229], v240, off offset:2048
	global_store_dword v[228:229], v241, off offset:2112
	global_store_dword v[228:229], v242, off offset:2176
	global_store_dword v[228:229], v243, off offset:2240
	v_or_b32_e32 v226, 16, v80
	v_ashrrev_i32_e32 v227, 31, v226
	v_lshlrev_b64 v[226:227], 12, v[226:227]
	v_lshl_add_u64 v[228:229], v[78:79], 0, v[226:227]
	v_mul_f32_e32 v8, v8, v70
	v_mul_f32_e32 v9, v9, v71
	v_mul_f32_e32 v58, v58, v70
	v_mul_f32_e32 v59, v59, v71
	v_mul_f32_e32 v42, v42, v70
	v_mul_f32_e32 v43, v43, v71
	v_mul_f32_e32 v24, v24, v70
	v_mul_f32_e32 v25, v25, v71
	v_cndmask_b32_e64 v230, v9, v8, s[6:7]
	v_cndmask_b32_e64 v231, v59, v58, s[6:7]
	v_cndmask_b32_e64 v232, v43, v42, s[6:7]
	v_cndmask_b32_e64 v233, v25, v24, s[6:7]
	v_mov_b32_dpp v234, v230 quad_perm:[1,0,3,2] row_mask:0xf bank_mask:0xf
	v_mov_b32_dpp v235, v231 quad_perm:[1,0,3,2] row_mask:0xf bank_mask:0xf
	v_mov_b32_dpp v236, v232 quad_perm:[1,0,3,2] row_mask:0xf bank_mask:0xf
	v_mov_b32_dpp v237, v233 quad_perm:[1,0,3,2] row_mask:0xf bank_mask:0xf
	v_cndmask_b32_e64 v238, v8, v234, s[6:7]
	v_cndmask_b32_e64 v239, v234, v9, s[6:7]
	v_cvt_pk_bf16_f32 v240, v238, v239
	v_cndmask_b32_e64 v238, v58, v235, s[6:7]
	v_cndmask_b32_e64 v239, v235, v59, s[6:7]
	v_cvt_pk_bf16_f32 v241, v238, v239
	v_cndmask_b32_e64 v238, v42, v236, s[6:7]
	v_cndmask_b32_e64 v239, v236, v43, s[6:7]
	v_cvt_pk_bf16_f32 v242, v238, v239
	v_cndmask_b32_e64 v238, v24, v237, s[6:7]
	v_cndmask_b32_e64 v239, v237, v25, s[6:7]
	v_cvt_pk_bf16_f32 v243, v238, v239
	global_store_dword v[228:229], v240, off offset:2048
	global_store_dword v[228:229], v241, off offset:2112
	global_store_dword v[228:229], v242, off offset:2176
	global_store_dword v[228:229], v243, off offset:2240
	v_or_b32_e32 v226, 18, v80
	v_ashrrev_i32_e32 v227, 31, v226
	v_lshlrev_b64 v[226:227], 12, v[226:227]
	v_lshl_add_u64 v[228:229], v[78:79], 0, v[226:227]
	v_mul_f32_e32 v10, v10, v72
	v_mul_f32_e32 v11, v11, v73
	v_mul_f32_e32 v60, v60, v72
	v_mul_f32_e32 v61, v61, v73
	v_mul_f32_e32 v44, v44, v72
	v_mul_f32_e32 v45, v45, v73
	v_mul_f32_e32 v26, v26, v72
	v_mul_f32_e32 v27, v27, v73
	v_cndmask_b32_e64 v230, v11, v10, s[6:7]
	v_cndmask_b32_e64 v231, v61, v60, s[6:7]
	v_cndmask_b32_e64 v232, v45, v44, s[6:7]
	v_cndmask_b32_e64 v233, v27, v26, s[6:7]
; DEVI int crow(int r, int hi) { return (r & 3) + 8 * (r >> 2) + 4 * hi; }
; template <bool MLA> ...
;     ...
; #pragma unroll
;     for (int r = 0; r < 16; ++r) { const int orow = first + crow(r, hi);
;       if (orow < nrows) {
; #pragma unroll
;         for (int d0 = 0; d0 < 4; ++d0) Ob[(long)orow * ldo + d0 * 32 + r32] = __float2bfloat16(o[d0][r] * rli[r]); } }
	v_mov_b32_dpp v234, v230 quad_perm:[1,0,3,2] row_mask:0xf bank_mask:0xf
	v_mov_b32_dpp v235, v231 quad_perm:[1,0,3,2] row_mask:0xf bank_mask:0xf
	v_mov_b32_dpp v236, v232 quad_perm:[1,0,3,2] row_mask:0xf bank_mask:0xf
	v_mov_b32_dpp v237, v233 quad_perm:[1,0,3,2] row_mask:0xf bank_mask:0xf
	v_cndmask_b32_e64 v238, v10, v234, s[6:7]
	v_cndmask_b32_e64 v239, v234, v11, s[6:7]
	v_cvt_pk_bf16_f32 v240, v238, v239
	v_cndmask_b32_e64 v238, v60, v235, s[6:7]
	v_cndmask_b32_e64 v239, v235, v61, s[6:7]
	v_cvt_pk_bf16_f32 v241, v238, v239
	v_cndmask_b32_e64 v238, v44, v236, s[6:7]
	v_cndmask_b32_e64 v239, v236, v45, s[6:7]
	v_cvt_pk_bf16_f32 v242, v238, v239
	v_cndmask_b32_e64 v238, v26, v237, s[6:7]
	v_cndmask_b32_e64 v239, v237, v27, s[6:7]
	v_cvt_pk_bf16_f32 v243, v238, v239
	global_store_dword v[228:229], v240, off offset:2048
	global_store_dword v[228:229], v241, off offset:2112
	global_store_dword v[228:229], v242, off offset:2176
	global_store_dword v[228:229], v243, off offset:2240
	v_or_b32_e32 v226, 24, v80
	v_ashrrev_i32_e32 v227, 31, v226
	v_lshlrev_b64 v[226:227], 12, v[226:227]
	v_lshl_add_u64 v[228:229], v[78:79], 0, v[226:227]
	v_mul_f32_e32 v12, v12, v66
	v_mul_f32_e32 v13, v13, v67
	v_mul_f32_e32 v62, v62, v66
	v_mul_f32_e32 v63, v63, v67
	v_mul_f32_e32 v46, v46, v66
	v_mul_f32_e32 v47, v47, v67
	v_mul_f32_e32 v28, v28, v66
	v_mul_f32_e32 v29, v29, v67
	v_cndmask_b32_e64 v230, v13, v12, s[6:7]
	v_cndmask_b32_e64 v231, v63, v62, s[6:7]
	v_cndmask_b32_e64 v232, v47, v46, s[6:7]
	v_cndmask_b32_e64 v233, v29, v28, s[6:7]
	v_mov_b32_dpp v234, v230 quad_perm:[1,0,3,2] row_mask:0xf bank_mask:0xf
	v_mov_b32_dpp v235, v231 quad_perm:[1,0,3,2] row_mask:0xf bank_mask:0xf
	v_mov_b32_dpp v236, v232 quad_perm:[1,0,3,2] row_mask:0xf bank_mask:0xf
	v_mov_b32_dpp v237, v233 quad_perm:[1,0,3,2] row_mask:0xf bank_mask:0xf
	v_cndmask_b32_e64 v238, v12, v234, s[6:7]
	v_cndmask_b32_e64 v239, v234, v13, s[6:7]
	v_cvt_pk_bf16_f32 v240, v238, v239
	v_cndmask_b32_e64 v238, v62, v235, s[6:7]
	v_cndmask_b32_e64 v239, v235, v63, s[6:7]
	v_cvt_pk_bf16_f32 v241, v238, v239
	v_cndmask_b32_e64 v238, v46, v236, s[6:7]
	v_cndmask_b32_e64 v239, v236, v47, s[6:7]
	v_cvt_pk_bf16_f32 v242, v238, v239
	v_cndmask_b32_e64 v238, v28, v237, s[6:7]
	v_cndmask_b32_e64 v239, v237, v29, s[6:7]
	v_cvt_pk_bf16_f32 v243, v238, v239
	global_store_dword v[228:229], v240, off offset:2048
	global_store_dword v[228:229], v241, off offset:2112
	global_store_dword v[228:229], v242, off offset:2176
	global_store_dword v[228:229], v243, off offset:2240
	v_or_b32_e32 v226, 26, v80
	v_ashrrev_i32_e32 v227, 31, v226
	v_lshlrev_b64 v[226:227], 12, v[226:227]
	v_lshl_add_u64 v[228:229], v[78:79], 0, v[226:227]
	v_mul_f32_e32 v14, v14, v68
	v_mul_f32_e32 v15, v15, v69
	v_mul_f32_e32 v64, v64, v68
	v_mul_f32_e32 v65, v65, v69
	v_mul_f32_e32 v48, v48, v68
	v_mul_f32_e32 v49, v49, v69
	v_mul_f32_e32 v30, v30, v68
	v_mul_f32_e32 v31, v31, v69
	v_cndmask_b32_e64 v230, v15, v14, s[6:7]
	v_cndmask_b32_e64 v231, v65, v64, s[6:7]
	v_cndmask_b32_e64 v232, v49, v48, s[6:7]
	v_cndmask_b32_e64 v233, v31, v30, s[6:7]
	v_mov_b32_dpp v234, v230 quad_perm:[1,0,3,2] row_mask:0xf bank_mask:0xf
	v_mov_b32_dpp v235, v231 quad_perm:[1,0,3,2] row_mask:0xf bank_mask:0xf
	v_mov_b32_dpp v236, v232 quad_perm:[1,0,3,2] row_mask:0xf bank_mask:0xf
	v_mov_b32_dpp v237, v233 quad_perm:[1,0,3,2] row_mask:0xf bank_mask:0xf
	v_cndmask_b32_e64 v238, v14, v234, s[6:7]
	v_cndmask_b32_e64 v239, v234, v15, s[6:7]
	v_cvt_pk_bf16_f32 v240, v238, v239
	v_cndmask_b32_e64 v238, v64, v235, s[6:7]
	v_cndmask_b32_e64 v239, v235, v65, s[6:7]
	v_cvt_pk_bf16_f32 v241, v238, v239
	v_cndmask_b32_e64 v238, v48, v236, s[6:7]
	v_cndmask_b32_e64 v239, v236, v49, s[6:7]
	v_cvt_pk_bf16_f32 v242, v238, v239
	v_cndmask_b32_e64 v238, v30, v237, s[6:7]
	v_cndmask_b32_e64 v239, v237, v31, s[6:7]
	v_cvt_pk_bf16_f32 v243, v238, v239
	global_store_dword v[228:229], v240, off offset:2048
	global_store_dword v[228:229], v241, off offset:2112
	global_store_dword v[228:229], v242, off offset:2176
	global_store_dword v[228:229], v243, off offset:2240

; template <bool MLA> ...
;     ...
;   int kt = nkt - 1;
;   TILE_DMA(kt * 64, 0);
;     ...
;     const int buf = it & 1;
;     asm volatile("s_waitcnt vmcnt(0)" ::: "memory");
;     __syncthreads();
;     if (kt > 0) TILE_DMA((kt - 1) * 64, buf ^ 1);
;     const int k0 = kt * 64;
;     if (k0 < bmax) {
.Lsbp_inactive:
	s_or_b64 exec, exec, s[8:9]
	s_cmp_lt_i32 s39, 1
	s_cbranch_scc1 .LBB0_427
	s_lshl_b32 s0, s13, 14
	s_xor_b32 s0, s0, 0x4000
	v_add_u32_e32 v34, s68, v172
	v_ashrrev_i32_e32 v35, 31, v34
	v_add_u32_e32 v32, s0, v156
	v_lshlrev_b64 v[34:35], 11, v[34:35]
	v_readfirstlane_b32 s0, v32
	v_lshl_add_u64 v[34:35], v[144:145], 0, v[34:35]
	s_mov_b32 m0, s0
	v_add_u32_e32 v36, 0x2000, v32
	global_load_lds_dwordx4 v[34:35], off
	v_add_u32_e32 v34, s68, v171
	v_ashrrev_i32_e32 v35, 31, v34
	v_lshlrev_b64 v[34:35], 11, v[34:35]
	v_readfirstlane_b32 s0, v36
	v_lshl_add_u64 v[34:35], v[144:145], 0, v[34:35]
	s_mov_b32 m0, s0
	v_add_u32_e32 v36, 0x8000, v32
	global_load_lds_dwordx4 v[34:35], off
	v_add_u32_e32 v34, s68, v170
	v_ashrrev_i32_e32 v35, 31, v34
	v_lshlrev_b64 v[34:35], 11, v[34:35]
	v_readfirstlane_b32 s0, v36
	v_lshl_add_u64 v[34:35], v[150:151], 0, v[34:35]
	s_mov_b32 m0, s0
	v_add_u32_e32 v32, 0xa000, v32
	global_load_lds_dwordx4 v[34:35], off
	v_add_u32_e32 v34, s68, v169
	v_ashrrev_i32_e32 v35, 31, v34
	v_lshlrev_b64 v[34:35], 11, v[34:35]
	v_readfirstlane_b32 s0, v32
	v_lshl_add_u64 v[34:35], v[152:153], 0, v[34:35]
	s_mov_b32 m0, s0
	s_nop 0
	global_load_lds_dwordx4 v[34:35], off
	s_branch .LBB0_427

; template <bool MLA> ...
;     ...
;   int kt = nkt - 1;
;   TILE_DMA(kt * 64, 0);
;     ...
;     const int buf = it & 1;
;     asm volatile("s_waitcnt vmcnt(0)" ::: "memory");
;     __syncthreads();
;     if (kt > 0) TILE_DMA((kt - 1) * 64, buf ^ 1);
;     const int k0 = kt * 64;
;     if (k0 < bmax) {
;       const char* Ks = K_lds + buf * SHM_K + r32 * KP;
;       f32x16 p0, p1;
; #pragma unroll
;       for (int r = 0; r < 16; ++r) { p0[r] = 0.f; p1[r] = 0.f; }
; #pragma unroll
;       for (int d0 = 0; d0 < ND0; ++d0) { const int off = kq4[d0 & 3] + (d0 >> 2) * 128;
;         bf16x8 b0 = *reinterpret_cast<const bf16x8*>(Ks + off);
;         bf16x8 b1 = *reinterpret_cast<const bf16x8*>(Ks + off + 32 * KP);
;         p0 = __builtin_amdgcn_mfma_f32_32x32x16_bf16(b0, qr[d0], p0, 0, 0, 0);
;         p1 = __builtin_amdgcn_mfma_f32_32x32x16_bf16(b1, qr[d0], p1, 0, 0, 0); }
.LBB0_430:
	s_add_i32 s12, s72, s68
	s_add_i32 s0, s12, 0xc0
	v_cmp_lt_i32_e64 s[0:1], s0, v161
	s_and_saveexec_b64 s[8:9], s[0:1]
	s_cbranch_execz .Lsbp_inactive
	s_lshl_b32 s73, s13, 14
	v_add_u32_e32 v32, s73, v166
	v_add_u32_e32 v42, v32, v162
	v_add_u32_e32 v43, v32, v163
	v_add_u32_e32 v44, v32, v164
	v_add_u32_e32 v32, v32, v165
	ds_read_b128 v[34:37], v42 offset:32768
	ds_read_b128 v[38:41], v42 offset:40960
	ds_read_b128 v[216:219], v43 offset:32768
	ds_read_b128 v[220:223], v43 offset:40960
	ds_read_b128 v[224:227], v44 offset:32768
	ds_read_b128 v[228:231], v44 offset:40960
	s_addk_i32 s12, 0x100
	v_cmp_le_i32_e64 s[0:1], s12, v160
	s_waitcnt lgkmcnt(5)
	v_mfma_f32_32x32x16_bf16 v[80:95], v[34:37], v[112:115], 0
	ds_read_b128 v[34:37], v32 offset:32768
	s_waitcnt lgkmcnt(5)
	v_mfma_f32_32x32x16_bf16 v[96:111], v[38:41], v[112:115], 0
	ds_read_b128 v[38:41], v32 offset:40960
	s_waitcnt lgkmcnt(5)
	v_mfma_f32_32x32x16_bf16 v[80:95], v[216:219], v[116:119], v[80:95]
	ds_read_b128 v[216:219], v42 offset:32896
	s_waitcnt lgkmcnt(5)
	v_mfma_f32_32x32x16_bf16 v[96:111], v[220:223], v[116:119], v[96:111]
	ds_read_b128 v[220:223], v42 offset:41088
	s_waitcnt lgkmcnt(5)
	v_mfma_f32_32x32x16_bf16 v[80:95], v[224:227], v[120:123], v[80:95]
	ds_read_b128 v[224:227], v43 offset:32896
	s_waitcnt lgkmcnt(5)
	v_mfma_f32_32x32x16_bf16 v[96:111], v[228:231], v[120:123], v[96:111]
	ds_read_b128 v[228:231], v43 offset:41088
	s_waitcnt lgkmcnt(5)
	v_mfma_f32_32x32x16_bf16 v[80:95], v[34:37], v[124:127], v[80:95]
	ds_read_b128 v[34:37], v44 offset:32896
	s_waitcnt lgkmcnt(5)
	v_mfma_f32_32x32x16_bf16 v[96:111], v[38:41], v[124:127], v[96:111]
	ds_read_b128 v[38:41], v44 offset:41088
	s_waitcnt lgkmcnt(5)
	v_mfma_f32_32x32x16_bf16 v[80:95], v[216:219], v[128:131], v[80:95]
	ds_read_b128 v[216:219], v32 offset:32896
	s_waitcnt lgkmcnt(5)
	v_mfma_f32_32x32x16_bf16 v[96:111], v[220:223], v[128:131], v[96:111]
	ds_read_b128 v[220:223], v32 offset:41088
	s_waitcnt lgkmcnt(5)
	v_mfma_f32_32x32x16_bf16 v[80:95], v[224:227], v[132:135], v[80:95]
	s_waitcnt lgkmcnt(4)
	v_mfma_f32_32x32x16_bf16 v[96:111], v[228:231], v[132:135], v[96:111]
	s_waitcnt lgkmcnt(3)
	v_mfma_f32_32x32x16_bf16 v[80:95], v[34:37], v[136:139], v[80:95]
	s_waitcnt lgkmcnt(2)
	v_mfma_f32_32x32x16_bf16 v[96:111], v[38:41], v[136:139], v[96:111]
	s_waitcnt lgkmcnt(1)
	v_mfma_f32_32x32x16_bf16 v[80:95], v[216:219], v[140:143], v[80:95]
	s_waitcnt lgkmcnt(0)
	v_mfma_f32_32x32x16_bf16 v[96:111], v[220:223], v[140:143], v[96:111]
	s_cmp_lt_i32 s39, 1
	s_cbranch_scc1 .Lsbp_nodma
	s_lshl_b32 s12, s13, 14
	s_xor_b32 s12, s12, 0x4000
	v_add_u32_e32 v234, s68, v172
	v_ashrrev_i32_e32 v235, 31, v234
	v_add_u32_e32 v232, s12, v156
	v_lshlrev_b64 v[234:235], 11, v[234:235]
	v_readfirstlane_b32 s12, v232
	v_lshl_add_u64 v[234:235], v[144:145], 0, v[234:235]
	s_mov_b32 m0, s12
	v_add_u32_e32 v236, 0x2000, v232
	global_load_lds_dwordx4 v[234:235], off
	v_add_u32_e32 v234, s68, v171
	v_ashrrev_i32_e32 v235, 31, v234
	v_lshlrev_b64 v[234:235], 11, v[234:235]
	v_readfirstlane_b32 s12, v236
	v_lshl_add_u64 v[234:235], v[144:145], 0, v[234:235]
	s_mov_b32 m0, s12
	v_add_u32_e32 v236, 0x8000, v232
	global_load_lds_dwordx4 v[234:235], off
	v_add_u32_e32 v234, s68, v170
	v_ashrrev_i32_e32 v235, 31, v234
	v_lshlrev_b64 v[234:235], 11, v[234:235]
	v_readfirstlane_b32 s12, v236
	v_lshl_add_u64 v[234:235], v[150:151], 0, v[234:235]
	s_mov_b32 m0, s12
	v_add_u32_e32 v232, 0xa000, v232
	global_load_lds_dwordx4 v[234:235], off
	v_add_u32_e32 v234, s68, v169
	v_ashrrev_i32_e32 v235, 31, v234
	v_lshlrev_b64 v[234:235], 11, v[234:235]
	v_readfirstlane_b32 s12, v232
	v_lshl_add_u64 v[234:235], v[152:153], 0, v[234:235]
	s_mov_b32 m0, s12
	s_nop 0
	global_load_lds_dwordx4 v[234:235], off
; template <bool MASK>
; DEVI void sb_half(f32x16& p, const int keybase, const int bound, const int hi, float& run) {
;   float om[16];
; #pragma unroll
;   for (int r = 0; r < 16; ++r) {
;     const float e = __builtin_amdgcn_exp2f(p[r]);
;     float q = __builtin_amdgcn_rcpf(1.f + e);
;     if (MASK) { const int key = keybase + (r & 3) + 8 * (r >> 2); q = key < bound ? q : 1.f; }
;     om[r] = q; }
;   float tot[4], par[4];
; #pragma unroll
;   for (int ri = 0; ri < 4; ++ri) { const float s0 = (om[4 * ri] * om[4 * ri + 1]) * (om[4 * ri + 2] * om[4 * ri + 3]);
;     par[ri] = partner_of(s0, hi); tot[ri] = s0 * par[ri]; }
; #pragma unroll
;     ...
;     float a = run * (hi == 0 ? par[ri] : 1.f);
; #pragma unroll
;     for (int e = 3; e >= 0; --e) { const int r = 4 * ri + e; const float an = a * om[r]; p[r] = a - an; a = an; }
;     run *= tot[ri];
;   }
; }
.Lsbp_nodma:
	s_nop 10
	v_exp_f32_e32 v183, v80
	v_exp_f32_e32 v182, v81
	v_exp_f32_e32 v181, v82
	v_exp_f32_e32 v180, v83
	v_exp_f32_e32 v179, v84
	v_exp_f32_e32 v178, v85
	v_exp_f32_e32 v177, v86
	v_exp_f32_e32 v205, v96
	v_exp_f32_e32 v203, v97
	v_exp_f32_e32 v206, v98
	v_exp_f32_e32 v204, v99
	v_exp_f32_e32 v202, v100
	v_exp_f32_e32 v201, v101
	v_exp_f32_e32 v200, v102
	v_exp_f32_e32 v198, v103
	v_exp_f32_e32 v196, v104
	v_exp_f32_e32 v199, v105
	v_exp_f32_e32 v197, v106
	v_exp_f32_e32 v195, v107
	v_exp_f32_e32 v194, v108
	v_exp_f32_e32 v193, v109
	v_exp_f32_e32 v192, v110
	v_exp_f32_e32 v154, v111
	v_exp_f32_e32 v176, v87
	v_exp_f32_e32 v175, v88
	v_exp_f32_e32 v174, v89
	v_exp_f32_e32 v173, v90
	v_exp_f32_e32 v111, v91
	v_exp_f32_e32 v110, v92
	v_exp_f32_e32 v109, v93
	v_exp_f32_e32 v85, v94
	v_exp_f32_e32 v47, v95
	s_and_saveexec_b64 s[12:13], s[0:1]
	s_xor_b64 s[0:1], exec, s[12:13]
	s_cbranch_execz .LBB0_433
	v_add_f32_e32 v32, 1.0, v205
	v_rcp_f32_e32 v86, v32
	v_add_f32_e32 v32, 1.0, v203
	v_rcp_f32_e32 v88, v32
	v_add_f32_e32 v32, 1.0, v206
	v_rcp_f32_e32 v87, v32
	v_add_f32_e32 v32, 1.0, v204
	v_rcp_f32_e32 v89, v32
	v_add_f32_e32 v32, 1.0, v202
	v_add_f32_e32 v34, 1.0, v195
	v_rcp_f32_e32 v38, v32
	v_add_f32_e32 v32, 1.0, v201
	v_rcp_f32_e32 v46, v34
	v_add_f32_e32 v34, 1.0, v194
	v_rcp_f32_e32 v40, v32
	v_add_f32_e32 v32, 1.0, v200
	v_rcp_f32_e32 v80, v34
	v_add_f32_e32 v34, 1.0, v193
	v_rcp_f32_e32 v39, v32
	v_add_f32_e32 v32, 1.0, v198
	v_rcp_f32_e32 v82, v34
	v_add_f32_e32 v34, 1.0, v192
	v_rcp_f32_e32 v41, v32
	v_rcp_f32_e32 v81, v34
	v_add_f32_e32 v34, 1.0, v154
	v_rcp_f32_e32 v83, v34
	v_pk_mul_f32 v[34:35], v[86:87], v[88:89]
	v_add_f32_e32 v32, 1.0, v196
	v_pk_mul_f32 v[106:107], v[34:35], v[34:35] op_sel:[0,1] op_sel_hi:[1,0]
	v_rcp_f32_e32 v42, v32
	v_add_f32_e32 v32, 1.0, v199
	v_mov_b32_e32 v34, v106
	v_mov_b32_e32 v35, v106
	v_rcp_f32_e32 v44, v32
	s_nop 0
	v_permlane32_swap_b32_e32 v34, v35
	v_pk_mul_f32 v[36:37], v[38:39], v[40:41]
	v_cndmask_b32_e64 v35, v34, v35, s[6:7]
	v_mul_f32_e32 v34, v36, v37
	v_add_f32_e32 v32, 1.0, v197
	v_mov_b32_e32 v36, v34
	v_mov_b32_e32 v37, v34
	v_pk_mul_f32 v[92:93], v[80:81], v[82:83]
	v_rcp_f32_e32 v32, v32
	v_permlane32_swap_b32_e32 v36, v37
	v_mov_b32_e32 v43, v92
	v_mov_b32_e32 v45, v93
	v_cndmask_b32_e64 v36, v36, v37, s[6:7]
	v_pk_mul_f32 v[92:93], v[42:43], v[44:45]
	v_mul_f32_e32 v37, v34, v36
	v_mov_b32_e32 v34, v93
	v_mov_b32_e32 v43, v93
	s_nop 1
	v_permlane32_swap_b32_e32 v34, v43
	v_mul_f32_e32 v90, v32, v46
	v_cndmask_b32_e64 v91, v34, v43, s[6:7]
	v_pk_mul_f32 v[92:93], v[92:93], v[90:91]
	s_nop 0
	v_mov_b32_e32 v34, v92
	v_mov_b32_e32 v43, v92
	s_nop 1
	v_permlane32_swap_b32_e32 v34, v43
	v_cndmask_b32_e64 v154, v34, v43, s[6:7]
	v_cndmask_b32_e64 v34, 1.0, v91, s[6:7]
	v_mul_f32_e32 v193, v155, v34
	v_mul_f32_e32 v192, v83, v193
	v_mul_f32_e32 v194, v81, v192
	v_mul_f32_e32 v196, v82, v194
	v_mul_f32_e32 v198, v80, v196
	v_pk_mul_f32 v[80:81], v[92:93], v[154:155]
	v_cndmask_b32_e64 v34, 1.0, v154, s[6:7]
	v_mul_f32_e32 v91, v34, v81
	v_mul_f32_e32 v90, v46, v91
	v_mul_f32_e32 v154, v32, v90
	v_pk_mul_f32 v[94:95], v[80:81], v[80:81] op_sel:[0,1] op_sel_hi:[1,0]
	v_cndmask_b32_e64 v32, 1.0, v36, s[6:7]
	v_mul_f32_e32 v203, v32, v94
	v_mul_f32_e32 v202, v41, v203
	v_mul_f32_e32 v204, v39, v202
	v_mul_f32_e32 v96, v40, v204
	v_add_f32_e32 v32, 1.0, v183
	v_mul_f32_e32 v206, v38, v96
	v_rcp_f32_e32 v38, v32
	v_add_f32_e32 v32, 1.0, v182
	v_rcp_f32_e32 v40, v32
	v_add_f32_e32 v32, 1.0, v181
	v_rcp_f32_e32 v39, v32
	v_add_f32_e32 v32, 1.0, v180
	v_rcp_f32_e32 v41, v32
	v_add_f32_e32 v32, 1.0, v179
	v_rcp_f32_e32 v43, v32
	v_add_f32_e32 v32, 1.0, v178
	v_rcp_f32_e32 v45, v32
	v_add_f32_e32 v32, 1.0, v177
	v_rcp_f32_e32 v81, v32
	v_add_f32_e32 v32, 1.0, v176
	v_mul_f32_e32 v92, v44, v154
	v_rcp_f32_e32 v83, v32
	v_add_f32_e32 v32, 1.0, v175
	v_mul_f32_e32 v200, v42, v92
	v_rcp_f32_e32 v42, v32
	v_add_f32_e32 v32, 1.0, v174
	v_rcp_f32_e32 v44, v32
	v_add_f32_e32 v32, 1.0, v173
	v_rcp_f32_e32 v80, v32
	v_add_f32_e32 v32, 1.0, v111
	v_rcp_f32_e32 v82, v32
	v_add_f32_e32 v32, 1.0, v110
	v_rcp_f32_e32 v46, v32
	v_add_f32_e32 v32, 1.0, v109
	v_rcp_f32_e32 v34, v32
	v_add_f32_e32 v32, 1.0, v85
	v_rcp_f32_e32 v36, v32
	v_add_f32_e32 v32, 1.0, v47
	v_pk_mul_f32 v[98:99], v[38:39], v[40:41]
	v_rcp_f32_e32 v84, v32
	v_mul_f32_e32 v32, v98, v99
	v_mov_b32_e32 v47, v32
	v_mov_b32_e32 v85, v32
	v_pk_mul_f32 v[98:99], v[42:43], v[44:45]
	v_pk_mul_f32 v[100:101], v[80:81], v[82:83]
	v_permlane32_swap_b32_e32 v47, v85
	v_pk_mul_f32 v[98:99], v[98:99], v[100:101]
	v_cndmask_b32_e64 v108, v47, v85, s[6:7]
	v_mov_b32_e32 v47, v99
	v_mov_b32_e32 v85, v99
	s_nop 1
	v_permlane32_swap_b32_e32 v47, v85
	v_cndmask_b32_e64 v105, v47, v85, s[6:7]
	v_mov_b32_e32 v85, v94
	v_cndmask_b32_e64 v95, 1.0, v35, s[6:7]
	v_mov_b32_e32 v100, v98
	v_mov_b32_e32 v101, v98
	v_pk_mul_f32 v[110:111], v[36:37], v[84:85]
	s_nop 0
	v_permlane32_swap_b32_e32 v100, v101
	v_mul_f32_e32 v95, v95, v111
	v_cndmask_b32_e64 v104, v100, v101, s[6:7]
	v_mul_f32_e32 v94, v89, v95
	v_mov_b32_e32 v47, v106
	v_pk_mul_f32 v[102:103], v[98:99], v[104:105]
	v_mul_f32_e32 v98, v87, v94
	v_pk_mul_f32 v[106:107], v[46:47], v[34:35]
	v_mul_f32_e32 v88, v88, v98
	v_pk_mul_f32 v[106:107], v[106:107], v[110:111]
	v_mov_b32_e32 v195, v192
	v_mov_b32_e32 v197, v194
	v_mov_b32_e32 v199, v196
	v_mov_b32_e32 v155, v90
	v_mov_b32_e32 v93, v154
	v_mov_b32_e32 v201, v92
	v_mov_b32_e32 v205, v202
	v_mov_b32_e32 v97, v204
	v_mov_b32_e32 v207, v96
	v_mov_b32_e32 v99, v94
	v_mul_f32_e32 v86, v86, v88
	v_mov_b32_e32 v89, v98
	v_mov_b32_e32 v87, v88
	v_mov_b32_e32 v35, v106
	v_mov_b32_e32 v37, v106
	v_mul_f32_e32 v32, v32, v108
	v_pk_add_f32 v[100:101], v[88:89], v[86:87] neg_lo:[0,1] neg_hi:[0,1]
	v_pk_add_f32 v[98:99], v[94:95], v[98:99] neg_lo:[0,1] neg_hi:[0,1]
	v_pk_add_f32 v[96:97], v[96:97], v[206:207] neg_lo:[0,1] neg_hi:[0,1]
	v_pk_add_f32 v[94:95], v[202:203], v[204:205] neg_lo:[0,1] neg_hi:[0,1]
	v_pk_add_f32 v[92:93], v[92:93], v[200:201] neg_lo:[0,1] neg_hi:[0,1]
	v_pk_add_f32 v[90:91], v[90:91], v[154:155] neg_lo:[0,1] neg_hi:[0,1]
	v_pk_add_f32 v[88:89], v[196:197], v[198:199] neg_lo:[0,1] neg_hi:[0,1]
	v_pk_add_f32 v[86:87], v[192:193], v[194:195] neg_lo:[0,1] neg_hi:[0,1]
	v_permlane32_swap_b32_e32 v35, v37

; DEVI int crow(int r, int hi) { return (r & 3) + 8 * (r >> 2) + 4 * hi; }
; template <bool MLA> ...
;     ...
;     } else {
; #pragma unroll
;       for (int r = 0; r < 16; ++r) rli[r] = 1.f;
;     }
; #pragma unroll
;     for (int r = 0; r < 16; ++r) { const int orow = first + crow(r, hi);
;       if (orow < nrows) {
; #pragma unroll
;         for (int d0 = 0; d0 < 4; ++d0) Ob[(long)orow * ldo + d0 * 32 + r32] = __float2bfloat16(o[d0][r] * rli[r]); } }
.LBB0_435:
	s_and_saveexec_b64 s[0:1], vcc
	s_cbranch_execz .LBB0_230
	v_readlane_b32 s6, v254, 47
	v_readlane_b32 s7, v254, 48
	s_lshl_b64 s[6:7], s[6:7], 12
	v_readlane_b32 s4, v255, 25
	s_add_u32 s6, s4, s6
	v_readlane_b32 s4, v255, 44
	s_addc_u32 s7, s4, s7
	s_lshl_b32 s8, s38, 1
	s_add_u32 s6, s6, s8
	s_addc_u32 s7, s7, 0
	v_or_b32_e32 v36, v159, v158
	v_lshlrev_b32_e32 v32, 1, v157
	v_lshl_add_u64 v[34:35], s[6:7], 0, v[32:33]
	s_mov_b32 s6, 0xaaaaaaaa
	s_mov_b32 s7, 0xaaaaaaaa
	v_mov_b32_e32 v80, 0xffe
	v_cndmask_b32_e64 v80, 0, v80, s[6:7]
	v_mov_b32_e32 v81, 0
	v_lshl_add_u64 v[34:35], v[34:35], 0, v[80:81]
	v_mov_b32_e32 v82, v36
	v_ashrrev_i32_e32 v83, 31, v82
	v_lshlrev_b64 v[82:83], 12, v[82:83]
	v_lshl_add_u64 v[84:85], v[34:35], 0, v[82:83]
	v_cndmask_b32_e64 v86, v49, v48, s[6:7]
	v_cndmask_b32_e64 v87, v65, v64, s[6:7]
	v_cndmask_b32_e64 v88, v1, v0, s[6:7]
	v_cndmask_b32_e64 v89, v17, v16, s[6:7]
	v_mov_b32_dpp v90, v86 quad_perm:[1,0,3,2] row_mask:0xf bank_mask:0xf
	v_mov_b32_dpp v91, v87 quad_perm:[1,0,3,2] row_mask:0xf bank_mask:0xf
	v_mov_b32_dpp v92, v88 quad_perm:[1,0,3,2] row_mask:0xf bank_mask:0xf
	v_mov_b32_dpp v93, v89 quad_perm:[1,0,3,2] row_mask:0xf bank_mask:0xf
	v_cndmask_b32_e64 v94, v48, v90, s[6:7]
	v_cndmask_b32_e64 v95, v90, v49, s[6:7]
	v_cvt_pk_bf16_f32 v96, v94, v95
	v_cndmask_b32_e64 v94, v64, v91, s[6:7]
	v_cndmask_b32_e64 v95, v91, v65, s[6:7]
	v_cvt_pk_bf16_f32 v97, v94, v95
	v_cndmask_b32_e64 v94, v0, v92, s[6:7]
	v_cndmask_b32_e64 v95, v92, v1, s[6:7]
	v_cvt_pk_bf16_f32 v98, v94, v95
	v_cndmask_b32_e64 v94, v16, v93, s[6:7]
	v_cndmask_b32_e64 v95, v93, v17, s[6:7]
	v_cvt_pk_bf16_f32 v99, v94, v95
	global_store_dword v[84:85], v96, off
	global_store_dword v[84:85], v97, off offset:64
	global_store_dword v[84:85], v98, off offset:128
	global_store_dword v[84:85], v99, off offset:192
	v_or_b32_e32 v82, 2, v36
	v_ashrrev_i32_e32 v83, 31, v82
	v_lshlrev_b64 v[82:83], 12, v[82:83]
	v_lshl_add_u64 v[84:85], v[34:35], 0, v[82:83]
	v_cndmask_b32_e64 v86, v51, v50, s[6:7]
	v_cndmask_b32_e64 v87, v67, v66, s[6:7]
	v_cndmask_b32_e64 v88, v3, v2, s[6:7]
	v_cndmask_b32_e64 v89, v19, v18, s[6:7]
	v_mov_b32_dpp v90, v86 quad_perm:[1,0,3,2] row_mask:0xf bank_mask:0xf
	v_mov_b32_dpp v91, v87 quad_perm:[1,0,3,2] row_mask:0xf bank_mask:0xf
	v_mov_b32_dpp v92, v88 quad_perm:[1,0,3,2] row_mask:0xf bank_mask:0xf
	v_mov_b32_dpp v93, v89 quad_perm:[1,0,3,2] row_mask:0xf bank_mask:0xf
	v_cndmask_b32_e64 v94, v50, v90, s[6:7]
	v_cndmask_b32_e64 v95, v90, v51, s[6:7]
	v_cvt_pk_bf16_f32 v96, v94, v95
	v_cndmask_b32_e64 v94, v66, v91, s[6:7]
	v_cndmask_b32_e64 v95, v91, v67, s[6:7]
	v_cvt_pk_bf16_f32 v97, v94, v95
	v_cndmask_b32_e64 v94, v2, v92, s[6:7]
	v_cndmask_b32_e64 v95, v92, v3, s[6:7]
	v_cvt_pk_bf16_f32 v98, v94, v95
	v_cndmask_b32_e64 v94, v18, v93, s[6:7]
	v_cndmask_b32_e64 v95, v93, v19, s[6:7]
	v_cvt_pk_bf16_f32 v99, v94, v95
	global_store_dword v[84:85], v96, off
	global_store_dword v[84:85], v97, off offset:64
	global_store_dword v[84:85], v98, off offset:128
	global_store_dword v[84:85], v99, off offset:192
	v_or_b32_e32 v82, 8, v36
	v_ashrrev_i32_e32 v83, 31, v82
	v_lshlrev_b64 v[82:83], 12, v[82:83]
	v_lshl_add_u64 v[84:85], v[34:35], 0, v[82:83]
	v_cndmask_b32_e64 v86, v53, v52, s[6:7]
	v_cndmask_b32_e64 v87, v69, v68, s[6:7]
	v_cndmask_b32_e64 v88, v5, v4, s[6:7]
	v_cndmask_b32_e64 v89, v21, v20, s[6:7]
	v_mov_b32_dpp v90, v86 quad_perm:[1,0,3,2] row_mask:0xf bank_mask:0xf
	v_mov_b32_dpp v91, v87 quad_perm:[1,0,3,2] row_mask:0xf bank_mask:0xf
	v_mov_b32_dpp v92, v88 quad_perm:[1,0,3,2] row_mask:0xf bank_mask:0xf
	v_mov_b32_dpp v93, v89 quad_perm:[1,0,3,2] row_mask:0xf bank_mask:0xf
	v_cndmask_b32_e64 v94, v52, v90, s[6:7]
	v_cndmask_b32_e64 v95, v90, v53, s[6:7]
	v_cvt_pk_bf16_f32 v96, v94, v95
	v_cndmask_b32_e64 v94, v68, v91, s[6:7]
	v_cndmask_b32_e64 v95, v91, v69, s[6:7]
	v_cvt_pk_bf16_f32 v97, v94, v95
	v_cndmask_b32_e64 v94, v4, v92, s[6:7]
	v_cndmask_b32_e64 v95, v92, v5, s[6:7]
	v_cvt_pk_bf16_f32 v98, v94, v95
	v_cndmask_b32_e64 v94, v20, v93, s[6:7]
	v_cndmask_b32_e64 v95, v93, v21, s[6:7]
	v_cvt_pk_bf16_f32 v99, v94, v95
	global_store_dword v[84:85], v96, off
	global_store_dword v[84:85], v97, off offset:64
	global_store_dword v[84:85], v98, off offset:128
	global_store_dword v[84:85], v99, off offset:192
	v_or_b32_e32 v82, 10, v36
	v_ashrrev_i32_e32 v83, 31, v82
	v_lshlrev_b64 v[82:83], 12, v[82:83]
	v_lshl_add_u64 v[84:85], v[34:35], 0, v[82:83]
	v_cndmask_b32_e64 v86, v55, v54, s[6:7]
	v_cndmask_b32_e64 v87, v71, v70, s[6:7]
	v_cndmask_b32_e64 v88, v7, v6, s[6:7]
	v_cndmask_b32_e64 v89, v23, v22, s[6:7]
	v_mov_b32_dpp v90, v86 quad_perm:[1,0,3,2] row_mask:0xf bank_mask:0xf
	v_mov_b32_dpp v91, v87 quad_perm:[1,0,3,2] row_mask:0xf bank_mask:0xf
	v_mov_b32_dpp v92, v88 quad_perm:[1,0,3,2] row_mask:0xf bank_mask:0xf
	v_mov_b32_dpp v93, v89 quad_perm:[1,0,3,2] row_mask:0xf bank_mask:0xf
	v_cndmask_b32_e64 v94, v54, v90, s[6:7]
	v_cndmask_b32_e64 v95, v90, v55, s[6:7]
	v_cvt_pk_bf16_f32 v96, v94, v95
	v_cndmask_b32_e64 v94, v70, v91, s[6:7]
	v_cndmask_b32_e64 v95, v91, v71, s[6:7]
	v_cvt_pk_bf16_f32 v97, v94, v95
	v_cndmask_b32_e64 v94, v6, v92, s[6:7]
	v_cndmask_b32_e64 v95, v92, v7, s[6:7]
	v_cvt_pk_bf16_f32 v98, v94, v95
; DEVI int crow(int r, int hi) { return (r & 3) + 8 * (r >> 2) + 4 * hi; }
; template <bool MLA> ...
;     ...
;     } else {
; #pragma unroll
;       for (int r = 0; r < 16; ++r) rli[r] = 1.f;
;     }
; #pragma unroll
;     for (int r = 0; r < 16; ++r) { const int orow = first + crow(r, hi);
;       if (orow < nrows) {
; #pragma unroll
;         for (int d0 = 0; d0 < 4; ++d0) Ob[(long)orow * ldo + d0 * 32 + r32] = __float2bfloat16(o[d0][r] * rli[r]); } }
	v_cndmask_b32_e64 v94, v22, v93, s[6:7]
	v_cndmask_b32_e64 v95, v93, v23, s[6:7]
	v_cvt_pk_bf16_f32 v99, v94, v95
	global_store_dword v[84:85], v96, off
	global_store_dword v[84:85], v97, off offset:64
	global_store_dword v[84:85], v98, off offset:128
	global_store_dword v[84:85], v99, off offset:192
	v_or_b32_e32 v82, 16, v36
	v_ashrrev_i32_e32 v83, 31, v82
	v_lshlrev_b64 v[82:83], 12, v[82:83]
	v_lshl_add_u64 v[84:85], v[34:35], 0, v[82:83]
	v_cndmask_b32_e64 v86, v57, v56, s[6:7]
	v_cndmask_b32_e64 v87, v73, v72, s[6:7]
	v_cndmask_b32_e64 v88, v9, v8, s[6:7]
	v_cndmask_b32_e64 v89, v25, v24, s[6:7]
	v_mov_b32_dpp v90, v86 quad_perm:[1,0,3,2] row_mask:0xf bank_mask:0xf
	v_mov_b32_dpp v91, v87 quad_perm:[1,0,3,2] row_mask:0xf bank_mask:0xf
	v_mov_b32_dpp v92, v88 quad_perm:[1,0,3,2] row_mask:0xf bank_mask:0xf
	v_mov_b32_dpp v93, v89 quad_perm:[1,0,3,2] row_mask:0xf bank_mask:0xf
	v_cndmask_b32_e64 v94, v56, v90, s[6:7]
	v_cndmask_b32_e64 v95, v90, v57, s[6:7]
	v_cvt_pk_bf16_f32 v96, v94, v95
	v_cndmask_b32_e64 v94, v72, v91, s[6:7]
	v_cndmask_b32_e64 v95, v91, v73, s[6:7]
	v_cvt_pk_bf16_f32 v97, v94, v95
	v_cndmask_b32_e64 v94, v8, v92, s[6:7]
	v_cndmask_b32_e64 v95, v92, v9, s[6:7]
	v_cvt_pk_bf16_f32 v98, v94, v95
	v_cndmask_b32_e64 v94, v24, v93, s[6:7]
	v_cndmask_b32_e64 v95, v93, v25, s[6:7]
	v_cvt_pk_bf16_f32 v99, v94, v95
	global_store_dword v[84:85], v96, off
	global_store_dword v[84:85], v97, off offset:64
	global_store_dword v[84:85], v98, off offset:128
	global_store_dword v[84:85], v99, off offset:192
	v_or_b32_e32 v82, 18, v36
	v_ashrrev_i32_e32 v83, 31, v82
	v_lshlrev_b64 v[82:83], 12, v[82:83]
	v_lshl_add_u64 v[84:85], v[34:35], 0, v[82:83]
	v_cndmask_b32_e64 v86, v59, v58, s[6:7]
	v_cndmask_b32_e64 v87, v75, v74, s[6:7]
	v_cndmask_b32_e64 v88, v11, v10, s[6:7]
	v_cndmask_b32_e64 v89, v27, v26, s[6:7]
	v_mov_b32_dpp v90, v86 quad_perm:[1,0,3,2] row_mask:0xf bank_mask:0xf
	v_mov_b32_dpp v91, v87 quad_perm:[1,0,3,2] row_mask:0xf bank_mask:0xf
	v_mov_b32_dpp v92, v88 quad_perm:[1,0,3,2] row_mask:0xf bank_mask:0xf
	v_mov_b32_dpp v93, v89 quad_perm:[1,0,3,2] row_mask:0xf bank_mask:0xf
	v_cndmask_b32_e64 v94, v58, v90, s[6:7]
	v_cndmask_b32_e64 v95, v90, v59, s[6:7]
	v_cvt_pk_bf16_f32 v96, v94, v95
	v_cndmask_b32_e64 v94, v74, v91, s[6:7]
	v_cndmask_b32_e64 v95, v91, v75, s[6:7]
	v_cvt_pk_bf16_f32 v97, v94, v95
	v_cndmask_b32_e64 v94, v10, v92, s[6:7]
	v_cndmask_b32_e64 v95, v92, v11, s[6:7]
	v_cvt_pk_bf16_f32 v98, v94, v95
	v_cndmask_b32_e64 v94, v26, v93, s[6:7]
	v_cndmask_b32_e64 v95, v93, v27, s[6:7]
	v_cvt_pk_bf16_f32 v99, v94, v95
	global_store_dword v[84:85], v96, off
	global_store_dword v[84:85], v97, off offset:64
	global_store_dword v[84:85], v98, off offset:128
	global_store_dword v[84:85], v99, off offset:192
	v_or_b32_e32 v82, 24, v36
	v_ashrrev_i32_e32 v83, 31, v82
	v_lshlrev_b64 v[82:83], 12, v[82:83]
	v_lshl_add_u64 v[84:85], v[34:35], 0, v[82:83]
	v_cndmask_b32_e64 v86, v61, v60, s[6:7]
	v_cndmask_b32_e64 v87, v77, v76, s[6:7]
	v_cndmask_b32_e64 v88, v13, v12, s[6:7]
	v_cndmask_b32_e64 v89, v29, v28, s[6:7]
	v_mov_b32_dpp v90, v86 quad_perm:[1,0,3,2] row_mask:0xf bank_mask:0xf
	v_mov_b32_dpp v91, v87 quad_perm:[1,0,3,2] row_mask:0xf bank_mask:0xf
	v_mov_b32_dpp v92, v88 quad_perm:[1,0,3,2] row_mask:0xf bank_mask:0xf
	v_mov_b32_dpp v93, v89 quad_perm:[1,0,3,2] row_mask:0xf bank_mask:0xf
	v_cndmask_b32_e64 v94, v60, v90, s[6:7]
	v_cndmask_b32_e64 v95, v90, v61, s[6:7]
	v_cvt_pk_bf16_f32 v96, v94, v95
	v_cndmask_b32_e64 v94, v76, v91, s[6:7]
	v_cndmask_b32_e64 v95, v91, v77, s[6:7]
	v_cvt_pk_bf16_f32 v97, v94, v95
	v_cndmask_b32_e64 v94, v12, v92, s[6:7]
	v_cndmask_b32_e64 v95, v92, v13, s[6:7]
	v_cvt_pk_bf16_f32 v98, v94, v95
	v_cndmask_b32_e64 v94, v28, v93, s[6:7]
	v_cndmask_b32_e64 v95, v93, v29, s[6:7]
	v_cvt_pk_bf16_f32 v99, v94, v95
	global_store_dword v[84:85], v96, off
	global_store_dword v[84:85], v97, off offset:64
	global_store_dword v[84:85], v98, off offset:128
	global_store_dword v[84:85], v99, off offset:192
	v_or_b32_e32 v82, 26, v36
	v_ashrrev_i32_e32 v83, 31, v82
	v_lshlrev_b64 v[82:83], 12, v[82:83]
	v_lshl_add_u64 v[84:85], v[34:35], 0, v[82:83]
	v_cndmask_b32_e64 v86, v63, v62, s[6:7]
	v_cndmask_b32_e64 v87, v79, v78, s[6:7]
	v_cndmask_b32_e64 v88, v15, v14, s[6:7]
	v_cndmask_b32_e64 v89, v31, v30, s[6:7]
	v_mov_b32_dpp v90, v86 quad_perm:[1,0,3,2] row_mask:0xf bank_mask:0xf
	v_mov_b32_dpp v91, v87 quad_perm:[1,0,3,2] row_mask:0xf bank_mask:0xf
	v_mov_b32_dpp v92, v88 quad_perm:[1,0,3,2] row_mask:0xf bank_mask:0xf
	v_mov_b32_dpp v93, v89 quad_perm:[1,0,3,2] row_mask:0xf bank_mask:0xf
	v_cndmask_b32_e64 v94, v62, v90, s[6:7]
	v_cndmask_b32_e64 v95, v90, v63, s[6:7]
	v_cvt_pk_bf16_f32 v96, v94, v95
	v_cndmask_b32_e64 v94, v78, v91, s[6:7]
	v_cndmask_b32_e64 v95, v91, v79, s[6:7]
	v_cvt_pk_bf16_f32 v97, v94, v95
	v_cndmask_b32_e64 v94, v14, v92, s[6:7]
	v_cndmask_b32_e64 v95, v92, v15, s[6:7]
	v_cvt_pk_bf16_f32 v98, v94, v95
	v_cndmask_b32_e64 v94, v30, v93, s[6:7]
	v_cndmask_b32_e64 v95, v93, v31, s[6:7]
	v_cvt_pk_bf16_f32 v99, v94, v95
	global_store_dword v[84:85], v96, off
	global_store_dword v[84:85], v97, off offset:64
	global_store_dword v[84:85], v98, off offset:128
	global_store_dword v[84:85], v99, off offset:192
	s_branch .LBB0_230
